# strategy 8 (MFMA/LDS interleave): MLA PV stage reads its V^T fragments (ds_read_b64_tr_b16) three MFMAs ahead into dead P registers with counted lgkmcnt waits
# speedup vs baseline: 1.0042x; 1.0011x over previous
; __device__ __forceinline__ s16x4 vtr(lds_cptr p) { return __builtin_bit_cast(s16x4, __builtin_amdgcn_ds_read_tr16_b64_v4i16((ATT_LAS s16x4*)p)); }
; __device__ __forceinline__ bf16x8 cat8(s16x4 lo, s16x4 hi) { return (bf16x8){lo[0], lo[1], lo[2], lo[3], hi[0], hi[1], hi[2], hi[3]}; }
; __device__ __forceinline__ float xmax32(float x) { const auto rr = __builtin_amdgcn_permlane32_swap(__float_as_uint(x), __float_as_uint(x), false, false); return fmaxf(__uint_as_float(rr[0]), __uint_as_float(rr[1])); }
; template <int KEYS> __device__ __forceinline__ void pv_tile(f32x16 (&o)[2], lds_cptr vbase, const bf16x8 (&pf)[KEYS / 16], int lane) {
;     const int hi = lane >> 5, li = lane & 15;
;     lds_cptr vp = vbase + (4 * hi + (li >> 2)) * 64 + ((lane >> 4) & 1) * 32 + (lane & 3) * 8;
; #pragma unroll
;     for (int d0 = 0; d0 < 2; ++d0)
; #pragma unroll
;         for (int ks = 0; ks < KEYS / 16; ++ks) {
;             const s16x4 lo = vtr(vp + d0 * (KEYS * 64) + ks * 1024), hh = vtr(vp + d0 * (KEYS * 64) + ks * 1024 + 512);
;             o[d0] = __builtin_amdgcn_mfma_f32_32x32x16_bf16(cat8(lo, hh), pf[ks], o[d0], 0, 0, 0);
;         }
; }
; template <int DK, int MODE>
; __device__ __forceinline__ void attn_unit(const bf16_t* Q, int ldq, const bf16_t* K, int ldk, const bf16_t* V, int ldv, bf16_t* O, int ldo, int qb, char* shm, float sc) {
;     ...
;             float rm = fmaxf(max16(p0), max16(p1)); rm = xmax32(rm);
;             const float mn = fmaxf(mrun, rm), f = __builtin_amdgcn_exp2f(mrun - mn); mrun = mn;
; #pragma unroll
;             for (int r = 0; r < 16; ++r) { p0[r] = __builtin_amdgcn_exp2f(p0[r] - mn); p1[r] = __builtin_amdgcn_exp2f(p1[r] - mn); }
;             lrun = lrun * f + (sum16(p0) + sum16(p1));
; #pragma unroll
;             for (int r = 0; r < 16; ++r) { o[0][r] *= f; o[1][r] *= f; }
.LBB0_1359:
	v_max_f32_e32 v32, v49, v49
	v_max_f32_e32 v33, v48, v48
	v_max_f32_e32 v32, v33, v32
	v_max_f32_e32 v33, v51, v51
	v_max_f32_e32 v34, v50, v50
	v_max_f32_e32 v33, v34, v33
	v_max_f32_e32 v34, v55, v55
	v_max_f32_e32 v35, v54, v54
	v_max_f32_e32 v34, v35, v34
	v_max_f32_e32 v35, v57, v57
	v_max_f32_e32 v38, v56, v56
	v_max_f32_e32 v35, v38, v35
	v_max_f32_e32 v38, v59, v59
	v_max_f32_e32 v39, v58, v58
	v_max_f32_e32 v38, v39, v38
	v_max_f32_e32 v39, v63, v63
	v_max_f32_e32 v42, v62, v62
	v_max_f32_e32 v39, v42, v39
	v_max3_f32 v34, v52, v53, v34
	v_max3_f32 v39, v60, v61, v39
	v_max3_f32 v32, v32, v33, v34
	v_max3_f32 v33, v35, v38, v39
	v_max_f32_e32 v34, v41, v41
	v_max_f32_e32 v35, v40, v40
	v_max_f32_e32 v34, v35, v34
	v_max_f32_e32 v35, v47, v47
	v_max_f32_e32 v38, v46, v46
	v_max_f32_e32 v35, v38, v35
	v_max_f32_e32 v38, v133, v133
	v_max_f32_e32 v39, v132, v132
	v_max_f32_e32 v38, v39, v38
	v_max_f32_e32 v39, v131, v131
	v_max_f32_e32 v42, v130, v130
	v_max_f32_e32 v39, v42, v39
	v_max_f32_e32 v42, v127, v127
	v_max_f32_e32 v43, v126, v126
	v_max_f32_e32 v42, v43, v42
	v_max3_f32 v42, v128, v129, v42
	v_max3_f32 v34, v36, v37, v34
	v_max3_f32 v35, v44, v45, v35
	v_max3_f32 v38, v38, v39, v42
	v_max3_f32 v34, v34, v35, v38
	v_max3_f32 v32, v32, v33, v34
	v_mov_b32_e32 v33, v32
	s_nop 1
	v_permlane32_swap_b32_e32 v32, v33
	v_max3_f32 v143, v142, v32, v33
	v_sub_f32_e32 v32, v48, v143
	v_exp_f32_e32 v33, v32
	v_sub_f32_e32 v32, v36, v143
	v_sub_f32_e32 v34, v49, v143
	v_sub_f32_e32 v36, v50, v143
	v_exp_f32_e32 v35, v34
	v_sub_f32_e32 v34, v37, v143
	v_exp_f32_e32 v37, v36
	v_sub_f32_e32 v36, v40, v143
	v_sub_f32_e32 v38, v51, v143
	v_sub_f32_e32 v40, v52, v143
	v_exp_f32_e32 v39, v38
	v_sub_f32_e32 v38, v41, v143
	v_exp_f32_e32 v41, v40
	v_sub_f32_e32 v40, v44, v143
	v_sub_f32_e32 v42, v53, v143
	v_sub_f32_e32 v44, v54, v143
	v_exp_f32_e32 v43, v42
	v_sub_f32_e32 v42, v45, v143
	v_exp_f32_e32 v45, v44
	v_sub_f32_e32 v44, v46, v143
	v_sub_f32_e32 v46, v55, v143
	v_exp_f32_e32 v32, v32
	v_exp_f32_e32 v34, v34
	v_exp_f32_e32 v36, v36
	v_exp_f32_e32 v38, v38
	v_exp_f32_e32 v49, v46
	v_sub_f32_e32 v46, v47, v143
	v_exp_f32_e32 v40, v40
	v_exp_f32_e32 v42, v42
	v_exp_f32_e32 v44, v44
	v_exp_f32_e32 v48, v46
	v_sub_f32_e32 v46, v56, v143
	v_sub_f32_e32 v50, v57, v143
	v_sub_f32_e32 v52, v58, v143
	v_sub_f32_e32 v54, v59, v143
	v_exp_f32_e32 v47, v46
	v_sub_f32_e32 v46, v132, v143
	v_exp_f32_e32 v51, v50
	v_sub_f32_e32 v50, v133, v143
	v_exp_f32_e32 v53, v52
	v_sub_f32_e32 v52, v130, v143
	v_exp_f32_e32 v55, v54
	v_sub_f32_e32 v54, v131, v143
	v_sub_f32_e32 v56, v60, v143
	v_sub_f32_e32 v58, v61, v143
	v_sub_f32_e32 v60, v62, v143
	v_sub_f32_e32 v62, v63, v143
	v_exp_f32_e32 v46, v46
	v_exp_f32_e32 v50, v50
	v_exp_f32_e32 v52, v52
	v_exp_f32_e32 v54, v54
	v_exp_f32_e32 v57, v56
	v_sub_f32_e32 v56, v128, v143
	v_exp_f32_e32 v59, v58
	v_sub_f32_e32 v58, v129, v143
	v_exp_f32_e32 v61, v60
	v_sub_f32_e32 v60, v126, v143
	v_exp_f32_e32 v63, v62
	v_sub_f32_e32 v62, v127, v143
	v_exp_f32_e32 v56, v56
	v_exp_f32_e32 v58, v58
	v_exp_f32_e32 v60, v60
	v_exp_f32_e32 v62, v62
	v_pk_add_f32 v[126:127], v[32:33], v[34:35]
	v_pk_add_f32 v[130:131], v[36:37], v[38:39]
	v_pk_add_f32 v[132:133], v[44:45], v[48:49]
	v_pk_add_f32 v[126:127], v[126:127], v[130:131]
	v_pk_add_f32 v[130:131], v[40:41], v[42:43]
	v_sub_f32_e32 v142, v142, v143
	v_pk_add_f32 v[130:131], v[130:131], v[132:133]
	v_pk_add_f32 v[132:133], v[52:53], v[54:55]
	v_pk_add_f32 v[126:127], v[126:127], v[130:131]
	v_pk_add_f32 v[130:131], v[46:47], v[50:51]
	v_pk_add_f32 v[144:145], v[60:61], v[62:63]
	v_pk_add_f32 v[130:131], v[130:131], v[132:133]
	v_pk_add_f32 v[132:133], v[56:57], v[58:59]
	v_exp_f32_e32 v128, v142
	v_pk_add_f32 v[132:133], v[132:133], v[144:145]
	v_mov_b32_e32 v142, v143
	v_pk_add_f32 v[130:131], v[130:131], v[132:133]
	v_pk_mul_f32 v[30:31], v[30:31], v[128:129] op_sel_hi:[1,0]
	v_pk_add_f32 v[126:127], v[126:127], v[130:131]
	v_pk_mul_f32 v[28:29], v[28:29], v[128:129] op_sel_hi:[1,0]
	v_add_f32_e32 v126, v126, v127
	v_fmac_f32_e32 v126, v141, v128
	v_pk_mul_f32 v[26:27], v[26:27], v[128:129] op_sel_hi:[1,0]
	v_pk_mul_f32 v[24:25], v[24:25], v[128:129] op_sel_hi:[1,0]
	v_pk_mul_f32 v[22:23], v[22:23], v[128:129] op_sel_hi:[1,0]
	v_pk_mul_f32 v[20:21], v[20:21], v[128:129] op_sel_hi:[1,0]
	v_pk_mul_f32 v[18:19], v[18:19], v[128:129] op_sel_hi:[1,0]
	v_pk_mul_f32 v[16:17], v[16:17], v[128:129] op_sel_hi:[1,0]
	v_pk_mul_f32 v[14:15], v[14:15], v[128:129] op_sel_hi:[1,0]
	v_pk_mul_f32 v[12:13], v[12:13], v[128:129] op_sel_hi:[1,0]
	v_pk_mul_f32 v[10:11], v[10:11], v[128:129] op_sel_hi:[1,0]
	v_pk_mul_f32 v[8:9], v[8:9], v[128:129] op_sel_hi:[1,0]
	v_pk_mul_f32 v[6:7], v[6:7], v[128:129] op_sel_hi:[1,0]
	v_pk_mul_f32 v[4:5], v[4:5], v[128:129] op_sel_hi:[1,0]
	v_pk_mul_f32 v[2:3], v[2:3], v[128:129] op_sel_hi:[1,0]
	v_pk_mul_f32 v[0:1], v[0:1], v[128:129] op_sel_hi:[1,0]
	v_cvt_pk_bf16_f32 v128, v33, v35
	v_cvt_pk_bf16_f32 v129, v37, v39
	v_cvt_pk_bf16_f32 v130, v41, v43
	v_cvt_pk_bf16_f32 v131, v45, v49
	v_cvt_pk_bf16_f32 v144, v47, v51
	v_cvt_pk_bf16_f32 v145, v53, v55
	v_cvt_pk_bf16_f32 v146, v57, v59
	v_cvt_pk_bf16_f32 v147, v61, v63
	v_cvt_pk_bf16_f32 v32, v32, v34
	v_cvt_pk_bf16_f32 v33, v36, v38
	v_cvt_pk_bf16_f32 v34, v40, v42
	v_cvt_pk_bf16_f32 v35, v44, v48
	v_add_u32_e32 v44, v135, v136
	v_cvt_pk_bf16_f32 v36, v46, v50
	v_cvt_pk_bf16_f32 v37, v52, v54
	v_cvt_pk_bf16_f32 v38, v56, v58
	v_cvt_pk_bf16_f32 v39, v60, v62
	ds_read_b64_tr_b16 v[40:41], v44 offset:34816
	ds_read_b64_tr_b16 v[42:43], v44 offset:35328
	ds_read_b64_tr_b16 v[48:49], v44 offset:35840
	ds_read_b64_tr_b16 v[50:51], v44 offset:36352
	ds_read_b64_tr_b16 v[52:53], v44 offset:36864
	ds_read_b64_tr_b16 v[54:55], v44 offset:37376
	ds_read_b64_tr_b16 v[56:57], v44 offset:37888
	ds_read_b64_tr_b16 v[58:59], v44 offset:38400
	v_mov_b32_e32 v141, v126
	s_waitcnt lgkmcnt(6)
	v_mfma_f32_32x32x16_bf16 v[16:31], v[40:43], v[128:131], v[16:31]
	ds_read_b64_tr_b16 v[40:41], v44 offset:38912
	ds_read_b64_tr_b16 v[42:43], v44 offset:39424
	s_waitcnt lgkmcnt(6)
	v_mfma_f32_32x32x16_bf16 v[16:31], v[48:51], v[144:147], v[16:31]
	ds_read_b64_tr_b16 v[48:49], v44 offset:39936
	ds_read_b64_tr_b16 v[50:51], v44 offset:40448
	s_waitcnt lgkmcnt(6)
	v_mfma_f32_32x32x16_bf16 v[16:31], v[52:55], v[32:35], v[16:31]
	ds_read_b64_tr_b16 v[52:53], v44 offset:40960
	ds_read_b64_tr_b16 v[54:55], v44 offset:41472
	s_waitcnt lgkmcnt(6)
	v_mfma_f32_32x32x16_bf16 v[16:31], v[56:59], v[36:39], v[16:31]
	ds_read_b64_tr_b16 v[56:57], v44 offset:41984
	ds_read_b64_tr_b16 v[58:59], v44 offset:42496
	s_waitcnt lgkmcnt(6)
	v_mfma_f32_32x32x16_bf16 v[0:15], v[40:43], v[128:131], v[0:15]
	s_waitcnt lgkmcnt(4)
	v_mfma_f32_32x32x16_bf16 v[0:15], v[48:51], v[144:147], v[0:15]
	s_waitcnt lgkmcnt(2)
	v_mfma_f32_32x32x16_bf16 v[0:15], v[52:55], v[32:35], v[0:15]
	s_waitcnt lgkmcnt(0)
	v_mfma_f32_32x32x16_bf16 v[0:15], v[56:59], v[36:39], v[0:15]

; __device__ __forceinline__ s16x4 vtr(lds_cptr p) { return __builtin_bit_cast(s16x4, __builtin_amdgcn_ds_read_tr16_b64_v4i16((ATT_LAS s16x4*)p)); }
; __device__ __forceinline__ bf16x8 cat8(s16x4 lo, s16x4 hi) { return (bf16x8){lo[0], lo[1], lo[2], lo[3], hi[0], hi[1], hi[2], hi[3]}; }
; __device__ __forceinline__ float xmax32(float x) { const auto rr = __builtin_amdgcn_permlane32_swap(__float_as_uint(x), __float_as_uint(x), false, false); return fmaxf(__uint_as_float(rr[0]), __uint_as_float(rr[1])); }
; template <int KEYS> __device__ __forceinline__ void pv_tile(f32x16 (&o)[2], lds_cptr vbase, const bf16x8 (&pf)[KEYS / 16], int lane) {
;     const int hi = lane >> 5, li = lane & 15;
;     lds_cptr vp = vbase + (4 * hi + (li >> 2)) * 64 + ((lane >> 4) & 1) * 32 + (lane & 3) * 8;
; #pragma unroll
;     for (int d0 = 0; d0 < 2; ++d0)
; #pragma unroll
;         for (int ks = 0; ks < KEYS / 16; ++ks) {
;             const s16x4 lo = vtr(vp + d0 * (KEYS * 64) + ks * 1024), hh = vtr(vp + d0 * (KEYS * 64) + ks * 1024 + 512);
;             o[d0] = __builtin_amdgcn_mfma_f32_32x32x16_bf16(cat8(lo, hh), pf[ks], o[d0], 0, 0, 0);
;         }
; }
; template <int DK, int MODE>
; __device__ __forceinline__ void attn_unit(const bf16_t* Q, int ldq, const bf16_t* K, int ldk, const bf16_t* V, int ldv, bf16_t* O, int ldo, int qb, char* shm, float sc) {
;     ...
;             float rm = fmaxf(max16(p0), max16(p1)); rm = xmax32(rm);
;             const float mn = fmaxf(mrun, rm), f = __builtin_amdgcn_exp2f(mrun - mn); mrun = mn;
; #pragma unroll
;             for (int r = 0; r < 16; ++r) { p0[r] = __builtin_amdgcn_exp2f(p0[r] - mn); p1[r] = __builtin_amdgcn_exp2f(p1[r] - mn); }
;             lrun = lrun * f + (sum16(p0) + sum16(p1));
; #pragma unroll
;             for (int r = 0; r < 16; ++r) { o[0][r] *= f; o[1][r] *= f; }
.LBB0_1368:
	v_max_f32_e32 v32, v49, v49
	v_max_f32_e32 v33, v48, v48
	v_max_f32_e32 v32, v33, v32
	v_max_f32_e32 v33, v51, v51
	v_max_f32_e32 v34, v50, v50
	v_max_f32_e32 v33, v34, v33
	v_max_f32_e32 v34, v55, v55
	v_max_f32_e32 v35, v54, v54
	v_max_f32_e32 v34, v35, v34
	v_max_f32_e32 v35, v57, v57
	v_max_f32_e32 v38, v56, v56
	v_max_f32_e32 v35, v38, v35
	v_max_f32_e32 v38, v59, v59
	v_max_f32_e32 v39, v58, v58
	v_max_f32_e32 v38, v39, v38
	v_max_f32_e32 v39, v63, v63
	v_max_f32_e32 v42, v62, v62
	v_max_f32_e32 v39, v42, v39
	v_max3_f32 v34, v52, v53, v34
	v_max3_f32 v39, v60, v61, v39
	v_max3_f32 v32, v32, v33, v34
	v_max3_f32 v33, v35, v38, v39
	v_max_f32_e32 v34, v41, v41
	v_max_f32_e32 v35, v40, v40
	v_max_f32_e32 v34, v35, v34
	v_max_f32_e32 v35, v47, v47
	v_max_f32_e32 v38, v46, v46
	v_max_f32_e32 v35, v38, v35
	v_max_f32_e32 v38, v133, v133
	v_max_f32_e32 v39, v132, v132
	v_max_f32_e32 v38, v39, v38
	v_max_f32_e32 v39, v131, v131
	v_max_f32_e32 v42, v130, v130
	v_max_f32_e32 v39, v42, v39
	v_max_f32_e32 v42, v127, v127
	v_max_f32_e32 v43, v126, v126
	v_max_f32_e32 v42, v43, v42
	v_max3_f32 v42, v128, v129, v42
	v_max3_f32 v34, v36, v37, v34
	v_max3_f32 v35, v44, v45, v35
	v_max3_f32 v38, v38, v39, v42
	v_max3_f32 v34, v34, v35, v38
	v_max3_f32 v32, v32, v33, v34
	v_mov_b32_e32 v33, v32
	s_nop 1
	v_permlane32_swap_b32_e32 v32, v33
	v_max3_f32 v143, v142, v32, v33
	v_sub_f32_e32 v32, v48, v143
	v_exp_f32_e32 v33, v32
	v_sub_f32_e32 v32, v36, v143
	v_sub_f32_e32 v34, v49, v143
	v_sub_f32_e32 v36, v50, v143
	v_exp_f32_e32 v35, v34
	v_sub_f32_e32 v34, v37, v143
	v_exp_f32_e32 v37, v36
	v_sub_f32_e32 v36, v40, v143
	v_sub_f32_e32 v38, v51, v143
	v_sub_f32_e32 v40, v52, v143
	v_exp_f32_e32 v39, v38
	v_sub_f32_e32 v38, v41, v143
	v_exp_f32_e32 v41, v40
	v_sub_f32_e32 v40, v44, v143
	v_sub_f32_e32 v42, v53, v143
	v_sub_f32_e32 v44, v54, v143
	v_exp_f32_e32 v43, v42
	v_sub_f32_e32 v42, v45, v143
	v_exp_f32_e32 v45, v44
	v_sub_f32_e32 v44, v46, v143
	v_sub_f32_e32 v46, v55, v143
	v_exp_f32_e32 v32, v32
	v_exp_f32_e32 v34, v34
	v_exp_f32_e32 v36, v36
	v_exp_f32_e32 v38, v38
	v_exp_f32_e32 v49, v46
	v_sub_f32_e32 v46, v47, v143
	v_exp_f32_e32 v40, v40
	v_exp_f32_e32 v42, v42
	v_exp_f32_e32 v44, v44
	v_exp_f32_e32 v48, v46
	v_sub_f32_e32 v46, v56, v143
	v_sub_f32_e32 v50, v57, v143
	v_sub_f32_e32 v52, v58, v143
	v_sub_f32_e32 v54, v59, v143
	v_exp_f32_e32 v47, v46
	v_sub_f32_e32 v46, v132, v143
	v_exp_f32_e32 v51, v50
	v_sub_f32_e32 v50, v133, v143
	v_exp_f32_e32 v53, v52
	v_sub_f32_e32 v52, v130, v143
	v_exp_f32_e32 v55, v54
	v_sub_f32_e32 v54, v131, v143
	v_sub_f32_e32 v56, v60, v143
	v_sub_f32_e32 v58, v61, v143
	v_sub_f32_e32 v60, v62, v143
	v_sub_f32_e32 v62, v63, v143
	v_exp_f32_e32 v46, v46
	v_exp_f32_e32 v50, v50
	v_exp_f32_e32 v52, v52
	v_exp_f32_e32 v54, v54
	v_exp_f32_e32 v57, v56
	v_sub_f32_e32 v56, v128, v143
	v_exp_f32_e32 v59, v58
	v_sub_f32_e32 v58, v129, v143
	v_exp_f32_e32 v61, v60
	v_sub_f32_e32 v60, v126, v143
	v_exp_f32_e32 v63, v62
	v_sub_f32_e32 v62, v127, v143
	v_exp_f32_e32 v56, v56
	v_exp_f32_e32 v58, v58
	v_exp_f32_e32 v60, v60
	v_exp_f32_e32 v62, v62
	v_pk_add_f32 v[126:127], v[32:33], v[34:35]
	v_pk_add_f32 v[130:131], v[36:37], v[38:39]
	v_pk_add_f32 v[132:133], v[44:45], v[48:49]
	v_pk_add_f32 v[126:127], v[126:127], v[130:131]
	v_pk_add_f32 v[130:131], v[40:41], v[42:43]
	v_sub_f32_e32 v142, v142, v143
	v_pk_add_f32 v[130:131], v[130:131], v[132:133]
	v_pk_add_f32 v[132:133], v[52:53], v[54:55]
	v_pk_add_f32 v[126:127], v[126:127], v[130:131]
	v_pk_add_f32 v[130:131], v[46:47], v[50:51]
	v_pk_add_f32 v[144:145], v[60:61], v[62:63]
	v_pk_add_f32 v[130:131], v[130:131], v[132:133]
	v_pk_add_f32 v[132:133], v[56:57], v[58:59]
	v_exp_f32_e32 v128, v142
	v_pk_add_f32 v[132:133], v[132:133], v[144:145]
	v_mov_b32_e32 v142, v143
	v_pk_add_f32 v[130:131], v[130:131], v[132:133]
	v_pk_mul_f32 v[30:31], v[30:31], v[128:129] op_sel_hi:[1,0]
	v_pk_add_f32 v[126:127], v[126:127], v[130:131]
	v_pk_mul_f32 v[28:29], v[28:29], v[128:129] op_sel_hi:[1,0]
	v_add_f32_e32 v126, v126, v127
	v_fmac_f32_e32 v126, v141, v128
	v_pk_mul_f32 v[26:27], v[26:27], v[128:129] op_sel_hi:[1,0]
	v_pk_mul_f32 v[24:25], v[24:25], v[128:129] op_sel_hi:[1,0]
	v_pk_mul_f32 v[22:23], v[22:23], v[128:129] op_sel_hi:[1,0]
	v_pk_mul_f32 v[20:21], v[20:21], v[128:129] op_sel_hi:[1,0]
	v_pk_mul_f32 v[18:19], v[18:19], v[128:129] op_sel_hi:[1,0]
	v_pk_mul_f32 v[16:17], v[16:17], v[128:129] op_sel_hi:[1,0]
	v_pk_mul_f32 v[14:15], v[14:15], v[128:129] op_sel_hi:[1,0]
	v_pk_mul_f32 v[12:13], v[12:13], v[128:129] op_sel_hi:[1,0]
	v_pk_mul_f32 v[10:11], v[10:11], v[128:129] op_sel_hi:[1,0]
	v_pk_mul_f32 v[8:9], v[8:9], v[128:129] op_sel_hi:[1,0]
	v_pk_mul_f32 v[6:7], v[6:7], v[128:129] op_sel_hi:[1,0]
	v_pk_mul_f32 v[4:5], v[4:5], v[128:129] op_sel_hi:[1,0]
	v_pk_mul_f32 v[2:3], v[2:3], v[128:129] op_sel_hi:[1,0]
	v_pk_mul_f32 v[0:1], v[0:1], v[128:129] op_sel_hi:[1,0]
	v_cvt_pk_bf16_f32 v128, v33, v35
	v_cvt_pk_bf16_f32 v129, v37, v39
	v_cvt_pk_bf16_f32 v130, v41, v43
	v_cvt_pk_bf16_f32 v131, v45, v49
	v_cvt_pk_bf16_f32 v144, v47, v51
	v_cvt_pk_bf16_f32 v145, v53, v55
	v_cvt_pk_bf16_f32 v146, v57, v59
	v_cvt_pk_bf16_f32 v147, v61, v63
	v_cvt_pk_bf16_f32 v32, v32, v34
	v_cvt_pk_bf16_f32 v33, v36, v38
	v_cvt_pk_bf16_f32 v34, v40, v42
	v_cvt_pk_bf16_f32 v35, v44, v48
	v_add_u32_e32 v44, v135, v136
	v_cvt_pk_bf16_f32 v36, v46, v50
	v_cvt_pk_bf16_f32 v37, v52, v54
	v_cvt_pk_bf16_f32 v38, v56, v58
	v_cvt_pk_bf16_f32 v39, v60, v62
	ds_read_b64_tr_b16 v[40:41], v44 offset:13312
	ds_read_b64_tr_b16 v[42:43], v44 offset:13824
	ds_read_b64_tr_b16 v[48:49], v44 offset:14336
	ds_read_b64_tr_b16 v[50:51], v44 offset:14848
	ds_read_b64_tr_b16 v[52:53], v44 offset:15360
	ds_read_b64_tr_b16 v[54:55], v44 offset:15872
	ds_read_b64_tr_b16 v[56:57], v44 offset:16384
	ds_read_b64_tr_b16 v[58:59], v44 offset:16896
	v_mov_b32_e32 v141, v126
	s_waitcnt lgkmcnt(6)
	v_mfma_f32_32x32x16_bf16 v[16:31], v[40:43], v[128:131], v[16:31]
	ds_read_b64_tr_b16 v[40:41], v44 offset:17408
	ds_read_b64_tr_b16 v[42:43], v44 offset:17920
	s_waitcnt lgkmcnt(6)
	v_mfma_f32_32x32x16_bf16 v[16:31], v[48:51], v[144:147], v[16:31]
	ds_read_b64_tr_b16 v[48:49], v44 offset:18432
	ds_read_b64_tr_b16 v[50:51], v44 offset:18944
	s_waitcnt lgkmcnt(6)
	v_mfma_f32_32x32x16_bf16 v[16:31], v[52:55], v[32:35], v[16:31]
	ds_read_b64_tr_b16 v[52:53], v44 offset:19456
	ds_read_b64_tr_b16 v[54:55], v44 offset:19968
	s_waitcnt lgkmcnt(6)
	v_mfma_f32_32x32x16_bf16 v[16:31], v[56:59], v[36:39], v[16:31]
	ds_read_b64_tr_b16 v[56:57], v44 offset:20480
	ds_read_b64_tr_b16 v[58:59], v44 offset:20992
	s_waitcnt lgkmcnt(6)
	v_mfma_f32_32x32x16_bf16 v[0:15], v[40:43], v[128:131], v[0:15]
	s_waitcnt lgkmcnt(4)
	v_mfma_f32_32x32x16_bf16 v[0:15], v[48:51], v[144:147], v[0:15]
	s_waitcnt lgkmcnt(2)
	v_mfma_f32_32x32x16_bf16 v[0:15], v[52:55], v[32:35], v[0:15]
	s_waitcnt lgkmcnt(0)
	v_mfma_f32_32x32x16_bf16 v[0:15], v[56:59], v[36:39], v[0:15]
